# GEMM k-loops: first iteration's first MFMA group takes C=0 (peeled copy, jumps into the loop), 127 accumulator zeroing moves per tile removed
# baseline (speedup 1.0000x reference)
; #define MFMA(a, b, c) __builtin_amdgcn_mfma_f32_32x32x16_bf16((a), (b), (c), 0, 0, 0)
;     ...
;     auto issue_at = [&](int mm0, int nn0, int kt, int buf) {
;       char* lb = L0 + buf * BUFB;
; #pragma unroll
;       for (int i = 0; i < 4; ++i) {
;         const int seg = wv * 4 + i, row = seg * 8 + gl_row;
;         const int c = (lane & 7) ^ ((row >> 1) & 7);
;         const u16* ap = (kt < g.split) ? g.a0 + (size_t)(mm0 + row) * g.ld0 + kt * g.ks0 : g.a1 + (size_t)(mm0 + row) * g.ld1 + (kt - g.split) * 64;
;         __builtin_amdgcn_global_load_lds((const unsigned*)(ap + c * 8), (__attribute__((address_space(3))) unsigned*)(lb + seg * 1024 + lane * 16), 16, 0, 0);
;       }
; #pragma unroll
;       for (int i = 0; i < BN / 64; ++i) {
;         const int seg = wv * (BN / 64) + i, row = seg * 8 + gl_row;
;         const int c = (lane & 7) ^ ((row >> 1) & 7);
;         __builtin_amdgcn_global_load_lds((const unsigned*)(g.W + (size_t)(nn0 + row) * g.K + kt * 64 + c * 8),
;                                          (__attribute__((address_space(3))) unsigned*)(lb + 256 * 128 + seg * 1024 + lane * 16), 16, 0, 0);
;       }
;     };
;     auto issue = [&](int kt, int buf) { issue_at(m0, n0, kt, buf); };
;     auto compute2 = [&](int buf) {
;       const char* lb = L0 + buf * BUFB;
; #pragma unroll
;       for (int ks = 0; ks < 4; ++ks) {
;         const int c = ks * 2 + hh;
;         bf16x8 wf[2], xf[MI];
; #pragma unroll
;         for (int j = 0; j < 2; ++j) { const int r = wn * 64 + j * 32 + l32; wf[j] = *(const bf16x8*)(lb + 256 * 128 + r * 128 + ((c ^ ((r >> 1) & 7)) << 4)); }
; #pragma unroll
;         for (int i = 0; i < MI; ++i) { const int r = wm * (MI * 32) + i * 32 + l32; xf[i] = *(const bf16x8*)(lb + r * 128 + ((c ^ ((r >> 1) & 7)) << 4)); }
; #pragma unroll
;         for (int i = 0; i < MI; ++i) {
;           acc[i][0] = MFMA(wf[0], xf[i], acc[i][0]);
;           acc[i][1] = MFMA(wf[1], xf[i], acc[i][1]);
;         }
;       }
.LBB0_798:
	v_writelane_b32 v255, s60, 0
	v_writelane_b32 v255, s61, 1
	v_writelane_b32 v255, s62, 2
	v_writelane_b32 v255, s63, 3
	v_writelane_b32 v255, s64, 4
	v_add_u32_e32 v0, v168, v169
	v_add_u32_e32 v178, v160, v169
	v_add_u32_e32 v199, v162, v169
	v_add_u32_e32 v254, v166, v169
	s_nop 0
	v_readfirstlane_b32 s60, v0
	v_readfirstlane_b32 s61, v178
	v_readfirstlane_b32 s62, v199
	v_readfirstlane_b32 s63, v254
	s_and_b32 s14, s11, 0x10000
	s_xor_b32 s15, s14, 0x10000
	s_add_i32 s15, s15, 0
	s_add_i32 s14, s14, 0
	v_add_u32_e32 v0, s14, v175
	v_add_u32_e32 v176, v0, v171
	v_add_u32_e32 v0, v0, v170
	ds_read_b128 v[200:203], v176 offset:32768
	ds_read_b128 v[204:207], v176 offset:36864
	ds_read_b128 v[208:211], v0
	ds_read_b128 v[212:215], v0 offset:4096
	ds_read_b128 v[216:219], v0 offset:8192
	ds_read_b128 v[220:223], v0 offset:12288
	s_add_i32 s64, s15, 0x8000
	s_add_i32 m0, s15, s60
	v_lshl_add_u64 v[176:177], v[152:153], 0, s[2:3]
	global_load_lds_dwordx4 v[176:177], off
	s_add_i32 m0, s15, s61
	v_lshl_add_u64 v[176:177], v[150:151], 0, s[2:3]
	global_load_lds_dwordx4 v[176:177], off
	s_add_i32 m0, s15, s62
	v_lshl_add_u64 v[176:177], v[148:149], 0, s[2:3]
	global_load_lds_dwordx4 v[176:177], off
	s_add_i32 m0, s15, s63
	v_lshl_add_u64 v[176:177], v[146:147], 0, s[2:3]
	global_load_lds_dwordx4 v[176:177], off
	s_add_i32 m0, s64, s60
	v_lshl_add_u64 v[176:177], v[144:145], 0, s[2:3]
	global_load_lds_dwordx4 v[176:177], off
	s_add_i32 m0, s64, s61
	v_lshl_add_u64 v[176:177], v[142:143], 0, s[2:3]
	global_load_lds_dwordx4 v[176:177], off
	s_add_i32 m0, s64, s62
	v_lshl_add_u64 v[176:177], v[140:141], 0, s[2:3]
	global_load_lds_dwordx4 v[176:177], off
	s_add_i32 m0, s64, s63
	v_lshl_add_u64 v[176:177], v[138:139], 0, s[2:3]
	global_load_lds_dwordx4 v[176:177], off
	v_add_u32_e32 v0, s14, v174
	v_add_u32_e32 v176, v0, v171
	v_add_u32_e32 v0, v0, v170
	s_waitcnt lgkmcnt(3)
	v_mfma_f32_32x32x16_bf16 v[114:129], v[200:203], v[208:211], 0
	s_add_i32 s11, s11, 0x10000
	s_add_u32 s2, s2, 0x80
	s_addc_u32 s3, s3, 0
	s_cmpk_eq_i32 s2, 0x780
	ds_read_b128 v[224:227], v176 offset:32768
	v_mfma_f32_32x32x16_bf16 v[98:113], v[204:207], v[208:211], 0
	ds_read_b128 v[228:231], v176 offset:36864
	s_waitcnt lgkmcnt(4)
	v_mfma_f32_32x32x16_bf16 v[82:97], v[200:203], v[212:215], 0
	ds_read_b128 v[232:235], v0
	v_mfma_f32_32x32x16_bf16 v[66:81], v[204:207], v[212:215], 0
	ds_read_b128 v[240:243], v0 offset:4096
	s_waitcnt lgkmcnt(5)
	v_mfma_f32_32x32x16_bf16 v[50:65], v[200:203], v[216:219], 0
	ds_read_b128 v[244:247], v0 offset:8192
	v_mfma_f32_32x32x16_bf16 v[34:49], v[204:207], v[216:219], 0
	ds_read_b128 v[248:251], v0 offset:12288
	s_waitcnt lgkmcnt(6)
	v_mfma_f32_32x32x16_bf16 v[18:33], v[200:203], v[220:223], 0
	v_mfma_f32_32x32x16_bf16 v[2:17], v[204:207], v[220:223], 0
	s_branch .Lgemm_g1_798

; #define MFMA(a, b, c) __builtin_amdgcn_mfma_f32_32x32x16_bf16((a), (b), (c), 0, 0, 0)
;     ...
;     auto issue_at = [&](int mm0, int nn0, int kt, int buf) {
;       char* lb = L0 + buf * BUFB;
; #pragma unroll
;       for (int i = 0; i < 4; ++i) {
;         const int seg = wv * 4 + i, row = seg * 8 + gl_row;
;         const int c = (lane & 7) ^ ((row >> 1) & 7);
;         const u16* ap = (kt < g.split) ? g.a0 + (size_t)(mm0 + row) * g.ld0 + kt * g.ks0 : g.a1 + (size_t)(mm0 + row) * g.ld1 + (kt - g.split) * 64;
;         __builtin_amdgcn_global_load_lds((const unsigned*)(ap + c * 8), (__attribute__((address_space(3))) unsigned*)(lb + seg * 1024 + lane * 16), 16, 0, 0);
;       }
; #pragma unroll
;       for (int i = 0; i < BN / 64; ++i) {
;         const int seg = wv * (BN / 64) + i, row = seg * 8 + gl_row;
;         const int c = (lane & 7) ^ ((row >> 1) & 7);
;         __builtin_amdgcn_global_load_lds((const unsigned*)(g.W + (size_t)(nn0 + row) * g.K + kt * 64 + c * 8),
;                                          (__attribute__((address_space(3))) unsigned*)(lb + 256 * 128 + seg * 1024 + lane * 16), 16, 0, 0);
;       }
;     };
;     auto issue = [&](int kt, int buf) { issue_at(m0, n0, kt, buf); };
;     auto compute2 = [&](int buf) {
;       const char* lb = L0 + buf * BUFB;
; #pragma unroll
;       for (int ks = 0; ks < 4; ++ks) {
;         const int c = ks * 2 + hh;
;         bf16x8 wf[2], xf[MI];
; #pragma unroll
;         for (int j = 0; j < 2; ++j) { const int r = wn * 64 + j * 32 + l32; wf[j] = *(const bf16x8*)(lb + 256 * 128 + r * 128 + ((c ^ ((r >> 1) & 7)) << 4)); }
; #pragma unroll
;         for (int i = 0; i < MI; ++i) { const int r = wm * (MI * 32) + i * 32 + l32; xf[i] = *(const bf16x8*)(lb + r * 128 + ((c ^ ((r >> 1) & 7)) << 4)); }
; #pragma unroll
;         for (int i = 0; i < MI; ++i) {
;           acc[i][0] = MFMA(wf[0], xf[i], acc[i][0]);
;           acc[i][1] = MFMA(wf[1], xf[i], acc[i][1]);
;         }
;       }
.Lgemm_g1_798:
	v_add_u32_e32 v0, s14, v173
	v_add_u32_e32 v176, v0, v171
	v_add_u32_e32 v0, v0, v170
	s_waitcnt lgkmcnt(3)
	v_mfma_f32_32x32x16_bf16 v[114:129], v[224:227], v[232:235], v[114:129]
	ds_read_b128 v[200:203], v176 offset:32768
	v_mfma_f32_32x32x16_bf16 v[98:113], v[228:231], v[232:235], v[98:113]
	ds_read_b128 v[204:207], v176 offset:36864
	s_waitcnt lgkmcnt(4)
	v_mfma_f32_32x32x16_bf16 v[82:97], v[224:227], v[240:243], v[82:97]
	ds_read_b128 v[208:211], v0
	v_mfma_f32_32x32x16_bf16 v[66:81], v[228:231], v[240:243], v[66:81]
	ds_read_b128 v[212:215], v0 offset:4096
	s_waitcnt lgkmcnt(5)
	v_mfma_f32_32x32x16_bf16 v[50:65], v[224:227], v[244:247], v[50:65]
	ds_read_b128 v[216:219], v0 offset:8192
	v_mfma_f32_32x32x16_bf16 v[34:49], v[228:231], v[244:247], v[34:49]
	ds_read_b128 v[220:223], v0 offset:12288
	s_waitcnt lgkmcnt(6)
	v_mfma_f32_32x32x16_bf16 v[18:33], v[224:227], v[248:251], v[18:33]
	v_mfma_f32_32x32x16_bf16 v[2:17], v[228:231], v[248:251], v[2:17]
	v_add_u32_e32 v0, s14, v172
	v_add_u32_e32 v176, v0, v171
	v_add_u32_e32 v0, v0, v170
	s_waitcnt lgkmcnt(3)
	v_mfma_f32_32x32x16_bf16 v[114:129], v[200:203], v[208:211], v[114:129]
	ds_read_b128 v[224:227], v176 offset:32768
	v_mfma_f32_32x32x16_bf16 v[98:113], v[204:207], v[208:211], v[98:113]
	ds_read_b128 v[228:231], v176 offset:36864
	s_waitcnt lgkmcnt(4)
	v_mfma_f32_32x32x16_bf16 v[82:97], v[200:203], v[212:215], v[82:97]
	ds_read_b128 v[232:235], v0
	v_mfma_f32_32x32x16_bf16 v[66:81], v[204:207], v[212:215], v[66:81]
	ds_read_b128 v[240:243], v0 offset:4096
	s_waitcnt lgkmcnt(5)
	v_mfma_f32_32x32x16_bf16 v[50:65], v[200:203], v[216:219], v[50:65]
	ds_read_b128 v[244:247], v0 offset:8192
	v_mfma_f32_32x32x16_bf16 v[34:49], v[204:207], v[216:219], v[34:49]
	ds_read_b128 v[248:251], v0 offset:12288
	s_waitcnt lgkmcnt(6)
	v_mfma_f32_32x32x16_bf16 v[18:33], v[200:203], v[220:223], v[18:33]
	v_mfma_f32_32x32x16_bf16 v[2:17], v[204:207], v[220:223], v[2:17]
	s_waitcnt vmcnt(0)
	s_waitcnt vmcnt(0) lgkmcnt(0)
	s_barrier
	s_cbranch_scc1 .Lgemm_exit_798
	s_and_b32 s14, s11, 0x10000
	s_xor_b32 s15, s14, 0x10000
	s_add_i32 s15, s15, 0
	s_add_i32 s14, s14, 0
	v_add_u32_e32 v0, s14, v175
	v_add_u32_e32 v176, v0, v171
	v_add_u32_e32 v0, v0, v170
	ds_read_b128 v[200:203], v176 offset:32768
	ds_read_b128 v[204:207], v176 offset:36864
	ds_read_b128 v[208:211], v0
	ds_read_b128 v[212:215], v0 offset:4096
	ds_read_b128 v[216:219], v0 offset:8192
	ds_read_b128 v[220:223], v0 offset:12288
	v_mfma_f32_32x32x16_bf16 v[114:129], v[224:227], v[232:235], v[114:129]
	s_add_i32 s64, s15, 0x8000
	s_add_i32 m0, s15, s60
	v_lshl_add_u64 v[176:177], v[152:153], 0, s[2:3]
	global_load_lds_dwordx4 v[176:177], off
	v_mfma_f32_32x32x16_bf16 v[98:113], v[228:231], v[232:235], v[98:113]
	s_add_i32 m0, s15, s61
	v_lshl_add_u64 v[176:177], v[150:151], 0, s[2:3]
	global_load_lds_dwordx4 v[176:177], off
	s_add_i32 m0, s15, s62
	v_mfma_f32_32x32x16_bf16 v[82:97], v[224:227], v[240:243], v[82:97]
	v_lshl_add_u64 v[176:177], v[148:149], 0, s[2:3]
	global_load_lds_dwordx4 v[176:177], off
	s_add_i32 m0, s15, s63
	v_lshl_add_u64 v[176:177], v[146:147], 0, s[2:3]
	v_mfma_f32_32x32x16_bf16 v[66:81], v[228:231], v[240:243], v[66:81]
	global_load_lds_dwordx4 v[176:177], off
	s_add_i32 m0, s64, s60
	v_lshl_add_u64 v[176:177], v[144:145], 0, s[2:3]
	global_load_lds_dwordx4 v[176:177], off
	v_mfma_f32_32x32x16_bf16 v[50:65], v[224:227], v[244:247], v[50:65]
	s_add_i32 m0, s64, s61
	v_lshl_add_u64 v[176:177], v[142:143], 0, s[2:3]
	global_load_lds_dwordx4 v[176:177], off
	s_add_i32 m0, s64, s62
	v_mfma_f32_32x32x16_bf16 v[34:49], v[228:231], v[244:247], v[34:49]
	v_lshl_add_u64 v[176:177], v[140:141], 0, s[2:3]
	global_load_lds_dwordx4 v[176:177], off
	s_add_i32 m0, s64, s63
	v_lshl_add_u64 v[176:177], v[138:139], 0, s[2:3]
	v_mfma_f32_32x32x16_bf16 v[18:33], v[224:227], v[248:251], v[18:33]
	global_load_lds_dwordx4 v[176:177], off
	v_mfma_f32_32x32x16_bf16 v[2:17], v[228:231], v[248:251], v[2:17]
	s_branch .Lgemm_rot_798

; #define MFMA(a, b, c) __builtin_amdgcn_mfma_f32_32x32x16_bf16((a), (b), (c), 0, 0, 0)
;     ...
;     auto issue_at = [&](int mm0, int nn0, int kt, int buf) {
;       char* lb = L0 + buf * BUFB;
; #pragma unroll
;       for (int i = 0; i < 4; ++i) {
;         const int seg = wv * 4 + i, row = seg * 8 + gl_row;
;         const int c = (lane & 7) ^ ((row >> 1) & 7);
;         const u16* ap = (kt < g.split) ? g.a0 + (size_t)(mm0 + row) * g.ld0 + kt * g.ks0 : g.a1 + (size_t)(mm0 + row) * g.ld1 + (kt - g.split) * 64;
;         __builtin_amdgcn_global_load_lds((const unsigned*)(ap + c * 8), (__attribute__((address_space(3))) unsigned*)(lb + seg * 1024 + lane * 16), 16, 0, 0);
;       }
; #pragma unroll
;       for (int i = 0; i < BN / 64; ++i) {
;         const int seg = wv * (BN / 64) + i, row = seg * 8 + gl_row;
;         const int c = (lane & 7) ^ ((row >> 1) & 7);
;         __builtin_amdgcn_global_load_lds((const unsigned*)(g.W + (size_t)(nn0 + row) * g.K + kt * 64 + c * 8),
;                                          (__attribute__((address_space(3))) unsigned*)(lb + 256 * 128 + seg * 1024 + lane * 16), 16, 0, 0);
;       }
;     };
;     auto issue = [&](int kt, int buf) { issue_at(m0, n0, kt, buf); };
;     auto compute2 = [&](int buf) {
;       const char* lb = L0 + buf * BUFB;
; #pragma unroll
;       for (int ks = 0; ks < 4; ++ks) {
;         const int c = ks * 2 + hh;
;         bf16x8 wf[2], xf[MI];
; #pragma unroll
;         for (int j = 0; j < 2; ++j) { const int r = wn * 64 + j * 32 + l32; wf[j] = *(const bf16x8*)(lb + 256 * 128 + r * 128 + ((c ^ ((r >> 1) & 7)) << 4)); }
; #pragma unroll
;         for (int i = 0; i < MI; ++i) { const int r = wm * (MI * 32) + i * 32 + l32; xf[i] = *(const bf16x8*)(lb + r * 128 + ((c ^ ((r >> 1) & 7)) << 4)); }
; #pragma unroll
;         for (int i = 0; i < MI; ++i) {
;           acc[i][0] = MFMA(wf[0], xf[i], acc[i][0]);
;           acc[i][1] = MFMA(wf[1], xf[i], acc[i][1]);
;         }
;       }
.LBB0_1274:
	v_writelane_b32 v255, s62, 0
	v_writelane_b32 v255, s63, 1
	v_writelane_b32 v255, s64, 2
	v_writelane_b32 v255, s65, 3
	v_writelane_b32 v255, s66, 4
	v_add_u32_e32 v228, v177, v178
	v_add_u32_e32 v229, v169, v178
	v_add_u32_e32 v230, v170, v178
	v_add_u32_e32 v231, v172, v178
	s_nop 0
	v_readfirstlane_b32 s62, v228
	v_readfirstlane_b32 s63, v229
	v_readfirstlane_b32 s64, v230
	v_readfirstlane_b32 s65, v231
	s_and_b32 s59, s56, 0x10000
	s_xor_b32 s60, s59, 0x10000
	s_add_i32 s57, s58, 1
	s_add_i32 s60, s60, 0
	s_cmp_lt_u32 s58, 21
	s_cselect_b64 vcc, -1, 0
	v_add_u32_e32 v233, s59, v201
	v_add_u32_e32 v230, v233, v175
	v_add_u32_e32 v234, v233, v174
	ds_read_b128 v[202:205], v230 offset:32768
	ds_read_b128 v[206:209], v230 offset:36864
	ds_read_b128 v[210:213], v234
	ds_read_b128 v[214:217], v234 offset:4096
	ds_read_b128 v[218:221], v234 offset:8192
	ds_read_b128 v[222:225], v234 offset:12288
	s_add_i32 s66, s60, 0x8000
	v_lshl_add_u64 v[226:227], v[160:161], 0, s[2:3]
	v_lshl_add_u64 v[228:229], v[144:145], 0, s[2:3]
	v_cndmask_b32_e32 v227, v229, v227, vcc
	v_cndmask_b32_e32 v226, v228, v226, vcc
	v_lshl_add_u64 v[226:227], v[0:1], 1, v[226:227]
	s_add_i32 m0, s60, s62
	v_lshl_add_u64 v[228:229], v[142:143], 0, s[2:3]
	global_load_lds_dwordx4 v[226:227], off
	v_lshl_add_u64 v[226:227], v[158:159], 0, s[2:3]
	v_cndmask_b32_e32 v227, v229, v227, vcc
	v_cndmask_b32_e32 v226, v228, v226, vcc
	v_lshl_add_u64 v[226:227], v[130:131], 1, v[226:227]
	s_add_i32 m0, s60, s63
	v_lshl_add_u64 v[228:229], v[140:141], 0, s[2:3]
	global_load_lds_dwordx4 v[226:227], off
	v_lshl_add_u64 v[226:227], v[156:157], 0, s[2:3]
	v_cndmask_b32_e32 v227, v229, v227, vcc
	v_cndmask_b32_e32 v226, v228, v226, vcc
	v_lshl_add_u64 v[226:227], v[132:133], 1, v[226:227]
	s_add_i32 m0, s60, s64
	v_lshl_add_u64 v[228:229], v[138:139], 0, s[2:3]
	global_load_lds_dwordx4 v[226:227], off
	v_lshl_add_u64 v[226:227], v[154:155], 0, s[2:3]
	v_cndmask_b32_e32 v226, v228, v226, vcc
	v_cndmask_b32_e32 v227, v229, v227, vcc
	s_add_i32 m0, s60, s65
	v_lshl_add_u64 v[226:227], v[134:135], 1, v[226:227]
	global_load_lds_dwordx4 v[226:227], off
	s_add_i32 m0, s66, s62
	v_lshl_add_u64 v[226:227], v[146:147], 0, s[2:3]
	global_load_lds_dwordx4 v[226:227], off
	s_add_i32 m0, s66, s63
	v_lshl_add_u64 v[226:227], v[148:149], 0, s[2:3]
	global_load_lds_dwordx4 v[226:227], off
	s_add_i32 m0, s66, s64
	v_lshl_add_u64 v[226:227], v[150:151], 0, s[2:3]
	global_load_lds_dwordx4 v[226:227], off
	v_lshl_add_u64 v[226:227], v[152:153], 0, s[2:3]
	s_add_i32 m0, s66, s65
	s_add_i32 s58, s59, 0
	global_load_lds_dwordx4 v[226:227], off
	v_add_u32_e32 v233, s59, v200
	v_add_u32_e32 v230, v233, v175
	v_add_u32_e32 v234, v233, v174
	s_waitcnt lgkmcnt(3)
	v_mfma_f32_32x32x16_bf16 v[114:129], v[202:205], v[210:213], 0
	s_add_u32 s2, s2, 0x80
	s_addc_u32 s3, s3, 0
	s_add_i32 s56, s56, 0x10000
	s_cmpk_eq_i32 s2, 0x1580
	s_mov_b32 s58, s57
	ds_read_b128 v[240:243], v230 offset:32768
	v_mfma_f32_32x32x16_bf16 v[98:113], v[206:209], v[210:213], 0
	ds_read_b128 v[244:247], v230 offset:36864
	s_waitcnt lgkmcnt(4)
	v_mfma_f32_32x32x16_bf16 v[82:97], v[202:205], v[214:217], 0
	ds_read_b128 v[248:251], v234
	v_mfma_f32_32x32x16_bf16 v[66:81], v[206:209], v[214:217], 0
	ds_read_b128 v[214:217], v234 offset:4096
	s_waitcnt lgkmcnt(5)
	v_mfma_f32_32x32x16_bf16 v[50:65], v[202:205], v[218:221], 0
	v_mfma_f32_32x32x16_bf16 v[34:49], v[206:209], v[218:221], 0
	ds_read_b128 v[218:221], v234 offset:8192
	s_waitcnt lgkmcnt(5)
	v_mfma_f32_32x32x16_bf16 v[18:33], v[202:205], v[222:225], 0
	v_mfma_f32_32x32x16_bf16 v[2:17], v[206:209], v[222:225], 0
	ds_read_b128 v[222:225], v234 offset:12288
	s_branch .Lgemm_g1_1274

; #define MFMA(a, b, c) __builtin_amdgcn_mfma_f32_32x32x16_bf16((a), (b), (c), 0, 0, 0)
;     ...
;     auto issue_at = [&](int mm0, int nn0, int kt, int buf) {
;       char* lb = L0 + buf * BUFB;
; #pragma unroll
;       for (int i = 0; i < 4; ++i) {
;         const int seg = wv * 4 + i, row = seg * 8 + gl_row;
;         const int c = (lane & 7) ^ ((row >> 1) & 7);
;         const u16* ap = (kt < g.split) ? g.a0 + (size_t)(mm0 + row) * g.ld0 + kt * g.ks0 : g.a1 + (size_t)(mm0 + row) * g.ld1 + (kt - g.split) * 64;
;         __builtin_amdgcn_global_load_lds((const unsigned*)(ap + c * 8), (__attribute__((address_space(3))) unsigned*)(lb + seg * 1024 + lane * 16), 16, 0, 0);
;       }
; #pragma unroll
;       for (int i = 0; i < BN / 64; ++i) {
;         const int seg = wv * (BN / 64) + i, row = seg * 8 + gl_row;
;         const int c = (lane & 7) ^ ((row >> 1) & 7);
;         __builtin_amdgcn_global_load_lds((const unsigned*)(g.W + (size_t)(nn0 + row) * g.K + kt * 64 + c * 8),
;                                          (__attribute__((address_space(3))) unsigned*)(lb + 256 * 128 + seg * 1024 + lane * 16), 16, 0, 0);
;       }
;     };
;     auto issue = [&](int kt, int buf) { issue_at(m0, n0, kt, buf); };
;     auto compute2 = [&](int buf) {
;       const char* lb = L0 + buf * BUFB;
; #pragma unroll
;       for (int ks = 0; ks < 4; ++ks) {
;         const int c = ks * 2 + hh;
;         bf16x8 wf[2], xf[MI];
; #pragma unroll
;         for (int j = 0; j < 2; ++j) { const int r = wn * 64 + j * 32 + l32; wf[j] = *(const bf16x8*)(lb + 256 * 128 + r * 128 + ((c ^ ((r >> 1) & 7)) << 4)); }
; #pragma unroll
;         for (int i = 0; i < MI; ++i) { const int r = wm * (MI * 32) + i * 32 + l32; xf[i] = *(const bf16x8*)(lb + r * 128 + ((c ^ ((r >> 1) & 7)) << 4)); }
; #pragma unroll
;         for (int i = 0; i < MI; ++i) {
;           acc[i][0] = MFMA(wf[0], xf[i], acc[i][0]);
;           acc[i][1] = MFMA(wf[1], xf[i], acc[i][1]);
;         }
;       }
.Lgemm_g1_1274:
	v_add_u32_e32 v233, s59, v199
	v_add_u32_e32 v230, v233, v175
	v_add_u32_e32 v234, v233, v174
	s_waitcnt lgkmcnt(3)
	v_mfma_f32_32x32x16_bf16 v[114:129], v[240:243], v[248:251], v[114:129]
	ds_read_b128 v[202:205], v230 offset:32768
	v_mfma_f32_32x32x16_bf16 v[98:113], v[244:247], v[248:251], v[98:113]
	ds_read_b128 v[206:209], v230 offset:36864
	s_waitcnt lgkmcnt(4)
	v_mfma_f32_32x32x16_bf16 v[82:97], v[240:243], v[214:217], v[82:97]
	ds_read_b128 v[210:213], v234
	v_mfma_f32_32x32x16_bf16 v[66:81], v[244:247], v[214:217], v[66:81]
	ds_read_b128 v[214:217], v234 offset:4096
	s_waitcnt lgkmcnt(5)
	v_mfma_f32_32x32x16_bf16 v[50:65], v[240:243], v[218:221], v[50:65]
	v_mfma_f32_32x32x16_bf16 v[34:49], v[244:247], v[218:221], v[34:49]
	ds_read_b128 v[218:221], v234 offset:8192
	s_waitcnt lgkmcnt(5)
	v_mfma_f32_32x32x16_bf16 v[18:33], v[240:243], v[222:225], v[18:33]
	v_mfma_f32_32x32x16_bf16 v[2:17], v[244:247], v[222:225], v[2:17]
	ds_read_b128 v[222:225], v234 offset:12288
	v_add_u32_e32 v233, s59, v176
	v_add_u32_e32 v230, v233, v175
	v_add_u32_e32 v234, v233, v174
	s_waitcnt lgkmcnt(3)
	v_mfma_f32_32x32x16_bf16 v[114:129], v[202:205], v[210:213], v[114:129]
	ds_read_b128 v[240:243], v230 offset:32768
	v_mfma_f32_32x32x16_bf16 v[98:113], v[206:209], v[210:213], v[98:113]
	ds_read_b128 v[244:247], v230 offset:36864
	s_waitcnt lgkmcnt(4)
	v_mfma_f32_32x32x16_bf16 v[82:97], v[202:205], v[214:217], v[82:97]
	ds_read_b128 v[248:251], v234
	v_mfma_f32_32x32x16_bf16 v[66:81], v[206:209], v[214:217], v[66:81]
	ds_read_b128 v[214:217], v234 offset:4096
	s_waitcnt lgkmcnt(5)
	v_mfma_f32_32x32x16_bf16 v[50:65], v[202:205], v[218:221], v[50:65]
	v_mfma_f32_32x32x16_bf16 v[34:49], v[206:209], v[218:221], v[34:49]
	ds_read_b128 v[218:221], v234 offset:8192
	s_waitcnt lgkmcnt(5)
	v_mfma_f32_32x32x16_bf16 v[18:33], v[202:205], v[222:225], v[18:33]
	v_mfma_f32_32x32x16_bf16 v[2:17], v[206:209], v[222:225], v[2:17]
	ds_read_b128 v[222:225], v234 offset:12288
	s_waitcnt vmcnt(0)
	s_waitcnt vmcnt(0) lgkmcnt(0)
	s_barrier
	s_cbranch_scc1 .Lgemm_exit_1274
	s_and_b32 s59, s56, 0x10000
	s_xor_b32 s60, s59, 0x10000
	s_add_i32 s57, s58, 1
	s_add_i32 s60, s60, 0
	s_cmp_lt_u32 s58, 21
	s_cselect_b64 vcc, -1, 0
	v_add_u32_e32 v233, s59, v201
	v_add_u32_e32 v230, v233, v175
	v_add_u32_e32 v234, v233, v174
	ds_read_b128 v[202:205], v230 offset:32768
	ds_read_b128 v[206:209], v230 offset:36864
	ds_read_b128 v[210:213], v234
	v_mfma_f32_32x32x16_bf16 v[114:129], v[240:243], v[248:251], v[114:129]
	s_add_i32 s66, s60, 0x8000
	v_lshl_add_u64 v[226:227], v[160:161], 0, s[2:3]
	v_lshl_add_u64 v[228:229], v[144:145], 0, s[2:3]
	v_cndmask_b32_e32 v227, v229, v227, vcc
	v_cndmask_b32_e32 v226, v228, v226, vcc
	v_lshl_add_u64 v[226:227], v[0:1], 1, v[226:227]
	v_mfma_f32_32x32x16_bf16 v[98:113], v[244:247], v[248:251], v[98:113]
	s_add_i32 m0, s60, s62
	v_lshl_add_u64 v[228:229], v[142:143], 0, s[2:3]
	global_load_lds_dwordx4 v[226:227], off
	v_lshl_add_u64 v[226:227], v[158:159], 0, s[2:3]
	v_cndmask_b32_e32 v227, v229, v227, vcc
	v_cndmask_b32_e32 v226, v228, v226, vcc
	v_mfma_f32_32x32x16_bf16 v[82:97], v[240:243], v[214:217], v[82:97]
	v_lshl_add_u64 v[226:227], v[130:131], 1, v[226:227]
	s_add_i32 m0, s60, s63
	v_lshl_add_u64 v[228:229], v[140:141], 0, s[2:3]
	global_load_lds_dwordx4 v[226:227], off
	v_lshl_add_u64 v[226:227], v[156:157], 0, s[2:3]
	v_cndmask_b32_e32 v227, v229, v227, vcc
	v_mfma_f32_32x32x16_bf16 v[66:81], v[244:247], v[214:217], v[66:81]
	ds_read_b128 v[214:217], v234 offset:4096
	v_cndmask_b32_e32 v226, v228, v226, vcc
	v_lshl_add_u64 v[226:227], v[132:133], 1, v[226:227]
	s_add_i32 m0, s60, s64
	v_lshl_add_u64 v[228:229], v[138:139], 0, s[2:3]
	global_load_lds_dwordx4 v[226:227], off
	v_lshl_add_u64 v[226:227], v[154:155], 0, s[2:3]
	v_mfma_f32_32x32x16_bf16 v[50:65], v[240:243], v[218:221], v[50:65]
	v_cndmask_b32_e32 v226, v228, v226, vcc
	v_cndmask_b32_e32 v227, v229, v227, vcc
	s_add_i32 m0, s60, s65
	v_lshl_add_u64 v[226:227], v[134:135], 1, v[226:227]
	global_load_lds_dwordx4 v[226:227], off
	s_add_i32 m0, s66, s62
	v_mfma_f32_32x32x16_bf16 v[34:49], v[244:247], v[218:221], v[34:49]
	ds_read_b128 v[218:221], v234 offset:8192
	v_lshl_add_u64 v[226:227], v[146:147], 0, s[2:3]
	global_load_lds_dwordx4 v[226:227], off
	s_add_i32 m0, s66, s63
	v_lshl_add_u64 v[226:227], v[148:149], 0, s[2:3]
	global_load_lds_dwordx4 v[226:227], off
	s_add_i32 m0, s66, s64
	v_mfma_f32_32x32x16_bf16 v[18:33], v[240:243], v[222:225], v[18:33]
	v_lshl_add_u64 v[226:227], v[150:151], 0, s[2:3]
	global_load_lds_dwordx4 v[226:227], off
	v_lshl_add_u64 v[226:227], v[152:153], 0, s[2:3]
	s_add_i32 m0, s66, s65
	s_add_i32 s58, s59, 0
	global_load_lds_dwordx4 v[226:227], off
	v_mfma_f32_32x32x16_bf16 v[2:17], v[244:247], v[222:225], v[2:17]
	ds_read_b128 v[222:225], v234 offset:12288
	s_branch .Lgemm_rot_1274

; #define MFMA(a, b, c) __builtin_amdgcn_mfma_f32_32x32x16_bf16((a), (b), (c), 0, 0, 0)
;     ...
;     auto issue_at = [&](int mm0, int nn0, int kt, int buf) {
;       char* lb = L0 + buf * BUFB;
; #pragma unroll
;       for (int i = 0; i < 4; ++i) {
;         const int seg = wv * 4 + i, row = seg * 8 + gl_row;
;         const int c = (lane & 7) ^ ((row >> 1) & 7);
;         const u16* ap = (kt < g.split) ? g.a0 + (size_t)(mm0 + row) * g.ld0 + kt * g.ks0 : g.a1 + (size_t)(mm0 + row) * g.ld1 + (kt - g.split) * 64;
;         __builtin_amdgcn_global_load_lds((const unsigned*)(ap + c * 8), (__attribute__((address_space(3))) unsigned*)(lb + seg * 1024 + lane * 16), 16, 0, 0);
;       }
; #pragma unroll
;       for (int i = 0; i < BN / 64; ++i) {
;         const int seg = wv * (BN / 64) + i, row = seg * 8 + gl_row;
;         const int c = (lane & 7) ^ ((row >> 1) & 7);
;         __builtin_amdgcn_global_load_lds((const unsigned*)(g.W + (size_t)(nn0 + row) * g.K + kt * 64 + c * 8),
;                                          (__attribute__((address_space(3))) unsigned*)(lb + 256 * 128 + seg * 1024 + lane * 16), 16, 0, 0);
;       }
;     };
;     auto issue = [&](int kt, int buf) { issue_at(m0, n0, kt, buf); };
;     auto compute2 = [&](int buf) {
;       const char* lb = L0 + buf * BUFB;
; #pragma unroll
;       for (int ks = 0; ks < 4; ++ks) {
;         const int c = ks * 2 + hh;
;         bf16x8 wf[2], xf[MI];
; #pragma unroll
;         for (int j = 0; j < 2; ++j) { const int r = wn * 64 + j * 32 + l32; wf[j] = *(const bf16x8*)(lb + 256 * 128 + r * 128 + ((c ^ ((r >> 1) & 7)) << 4)); }
; #pragma unroll
;         for (int i = 0; i < MI; ++i) { const int r = wm * (MI * 32) + i * 32 + l32; xf[i] = *(const bf16x8*)(lb + r * 128 + ((c ^ ((r >> 1) & 7)) << 4)); }
; #pragma unroll
;         for (int i = 0; i < MI; ++i) {
;           acc[i][0] = MFMA(wf[0], xf[i], acc[i][0]);
;           acc[i][1] = MFMA(wf[1], xf[i], acc[i][1]);
;         }
;       }
.LBB0_1371:
	s_waitcnt vmcnt(16)
	s_barrier
	v_writelane_b32 v255, s60, 0
	v_writelane_b32 v255, s61, 1
	v_writelane_b32 v255, s62, 2
	v_writelane_b32 v255, s63, 3
	v_writelane_b32 v255, s64, 4
	v_add_u32_e32 v0, v167, v168
	v_add_u32_e32 v175, v157, v168
	v_add_u32_e32 v178, v159, v168
	v_add_u32_e32 v199, v165, v168
	s_nop 0
	v_readfirstlane_b32 s60, v0
	v_readfirstlane_b32 s61, v175
	v_readfirstlane_b32 s62, v178
	v_readfirstlane_b32 s63, v199
	s_and_b32 s17, s16, 0x10000
	s_xor_b32 s43, s17, 0x10000
	s_add_i32 s43, s43, 0
	s_add_i32 s17, s17, 0
	v_add_u32_e32 v0, s17, v174
	v_add_u32_e32 v175, v0, v170
	v_add_u32_e32 v0, v0, v169
	ds_read_b128 v[200:203], v175 offset:32768
	ds_read_b128 v[204:207], v175 offset:36864
	ds_read_b128 v[208:211], v0
	ds_read_b128 v[212:215], v0 offset:4096
	ds_read_b128 v[216:219], v0 offset:8192
	ds_read_b128 v[220:223], v0 offset:12288
	s_add_i32 s64, s43, 0x8000
	s_add_i32 m0, s43, s60
	v_lshl_add_u64 v[176:177], v[152:153], 0, s[10:11]
	global_load_lds_dwordx4 v[176:177], off
	s_add_i32 m0, s43, s61
	v_lshl_add_u64 v[176:177], v[150:151], 0, s[10:11]
	global_load_lds_dwordx4 v[176:177], off
	s_add_i32 m0, s43, s62
	v_lshl_add_u64 v[176:177], v[148:149], 0, s[10:11]
	global_load_lds_dwordx4 v[176:177], off
	s_add_i32 m0, s43, s63
	v_lshl_add_u64 v[176:177], v[146:147], 0, s[10:11]
	global_load_lds_dwordx4 v[176:177], off
	s_add_i32 m0, s64, s60
	v_lshl_add_u64 v[176:177], v[144:145], 0, s[10:11]
	global_load_lds_dwordx4 v[176:177], off
	s_add_i32 m0, s64, s61
	v_lshl_add_u64 v[176:177], v[142:143], 0, s[10:11]
	global_load_lds_dwordx4 v[176:177], off
	s_add_i32 m0, s64, s62
	v_lshl_add_u64 v[176:177], v[140:141], 0, s[10:11]
	global_load_lds_dwordx4 v[176:177], off
	s_add_i32 m0, s64, s63
	v_lshl_add_u64 v[176:177], v[138:139], 0, s[10:11]
	global_load_lds_dwordx4 v[176:177], off
	v_add_u32_e32 v0, s17, v173
	v_add_u32_e32 v175, v0, v170
	v_add_u32_e32 v0, v0, v169
	s_waitcnt lgkmcnt(3)
	v_mfma_f32_32x32x16_bf16 v[114:129], v[200:203], v[208:211], 0
	s_add_i32 s16, s16, 0x10000
	s_add_u32 s10, s10, 0x80
	s_addc_u32 s11, s11, 0
	s_cmpk_eq_i32 s10, 0x780
	ds_read_b128 v[224:227], v175 offset:32768
	v_mfma_f32_32x32x16_bf16 v[98:113], v[204:207], v[208:211], 0
	ds_read_b128 v[228:231], v175 offset:36864
	s_waitcnt lgkmcnt(4)
	v_mfma_f32_32x32x16_bf16 v[82:97], v[200:203], v[212:215], 0
	ds_read_b128 v[232:235], v0
	v_mfma_f32_32x32x16_bf16 v[66:81], v[204:207], v[212:215], 0
	ds_read_b128 v[240:243], v0 offset:4096
	s_waitcnt lgkmcnt(5)
	v_mfma_f32_32x32x16_bf16 v[50:65], v[200:203], v[216:219], 0
	ds_read_b128 v[244:247], v0 offset:8192
	v_mfma_f32_32x32x16_bf16 v[34:49], v[204:207], v[216:219], 0
	ds_read_b128 v[248:251], v0 offset:12288
	s_waitcnt lgkmcnt(6)
	v_mfma_f32_32x32x16_bf16 v[18:33], v[200:203], v[220:223], 0
	v_mfma_f32_32x32x16_bf16 v[2:17], v[204:207], v[220:223], 0
	s_branch .Lgemm_g1_1371

; #define MFMA(a, b, c) __builtin_amdgcn_mfma_f32_32x32x16_bf16((a), (b), (c), 0, 0, 0)
;     ...
;     auto issue_at = [&](int mm0, int nn0, int kt, int buf) {
;       char* lb = L0 + buf * BUFB;
; #pragma unroll
;       for (int i = 0; i < 4; ++i) {
;         const int seg = wv * 4 + i, row = seg * 8 + gl_row;
;         const int c = (lane & 7) ^ ((row >> 1) & 7);
;         const u16* ap = (kt < g.split) ? g.a0 + (size_t)(mm0 + row) * g.ld0 + kt * g.ks0 : g.a1 + (size_t)(mm0 + row) * g.ld1 + (kt - g.split) * 64;
;         __builtin_amdgcn_global_load_lds((const unsigned*)(ap + c * 8), (__attribute__((address_space(3))) unsigned*)(lb + seg * 1024 + lane * 16), 16, 0, 0);
;       }
; #pragma unroll
;       for (int i = 0; i < BN / 64; ++i) {
;         const int seg = wv * (BN / 64) + i, row = seg * 8 + gl_row;
;         const int c = (lane & 7) ^ ((row >> 1) & 7);
;         __builtin_amdgcn_global_load_lds((const unsigned*)(g.W + (size_t)(nn0 + row) * g.K + kt * 64 + c * 8),
;                                          (__attribute__((address_space(3))) unsigned*)(lb + 256 * 128 + seg * 1024 + lane * 16), 16, 0, 0);
;       }
;     };
;     auto issue = [&](int kt, int buf) { issue_at(m0, n0, kt, buf); };
;     auto compute2 = [&](int buf) {
;       const char* lb = L0 + buf * BUFB;
; #pragma unroll
;       for (int ks = 0; ks < 4; ++ks) {
;         const int c = ks * 2 + hh;
;         bf16x8 wf[2], xf[MI];
; #pragma unroll
;         for (int j = 0; j < 2; ++j) { const int r = wn * 64 + j * 32 + l32; wf[j] = *(const bf16x8*)(lb + 256 * 128 + r * 128 + ((c ^ ((r >> 1) & 7)) << 4)); }
; #pragma unroll
;         for (int i = 0; i < MI; ++i) { const int r = wm * (MI * 32) + i * 32 + l32; xf[i] = *(const bf16x8*)(lb + r * 128 + ((c ^ ((r >> 1) & 7)) << 4)); }
; #pragma unroll
;         for (int i = 0; i < MI; ++i) {
;           acc[i][0] = MFMA(wf[0], xf[i], acc[i][0]);
;           acc[i][1] = MFMA(wf[1], xf[i], acc[i][1]);
;         }
;       }
.Lgemm_g1_1371:
	v_add_u32_e32 v0, s17, v172
	v_add_u32_e32 v175, v0, v170
	v_add_u32_e32 v0, v0, v169
	s_waitcnt lgkmcnt(3)
	v_mfma_f32_32x32x16_bf16 v[114:129], v[224:227], v[232:235], v[114:129]
	ds_read_b128 v[200:203], v175 offset:32768
	v_mfma_f32_32x32x16_bf16 v[98:113], v[228:231], v[232:235], v[98:113]
	ds_read_b128 v[204:207], v175 offset:36864
	s_waitcnt lgkmcnt(4)
	v_mfma_f32_32x32x16_bf16 v[82:97], v[224:227], v[240:243], v[82:97]
	ds_read_b128 v[208:211], v0
	v_mfma_f32_32x32x16_bf16 v[66:81], v[228:231], v[240:243], v[66:81]
	ds_read_b128 v[212:215], v0 offset:4096
	s_waitcnt lgkmcnt(5)
	v_mfma_f32_32x32x16_bf16 v[50:65], v[224:227], v[244:247], v[50:65]
	ds_read_b128 v[216:219], v0 offset:8192
	v_mfma_f32_32x32x16_bf16 v[34:49], v[228:231], v[244:247], v[34:49]
	ds_read_b128 v[220:223], v0 offset:12288
	s_waitcnt lgkmcnt(6)
	v_mfma_f32_32x32x16_bf16 v[18:33], v[224:227], v[248:251], v[18:33]
	v_mfma_f32_32x32x16_bf16 v[2:17], v[228:231], v[248:251], v[2:17]
	v_add_u32_e32 v0, s17, v171
	v_add_u32_e32 v175, v0, v170
	v_add_u32_e32 v0, v0, v169
	s_waitcnt lgkmcnt(3)
	v_mfma_f32_32x32x16_bf16 v[114:129], v[200:203], v[208:211], v[114:129]
	ds_read_b128 v[224:227], v175 offset:32768
	v_mfma_f32_32x32x16_bf16 v[98:113], v[204:207], v[208:211], v[98:113]
	ds_read_b128 v[228:231], v175 offset:36864
	s_waitcnt lgkmcnt(4)
	v_mfma_f32_32x32x16_bf16 v[82:97], v[200:203], v[212:215], v[82:97]
	ds_read_b128 v[232:235], v0
	v_mfma_f32_32x32x16_bf16 v[66:81], v[204:207], v[212:215], v[66:81]
	ds_read_b128 v[240:243], v0 offset:4096
	s_waitcnt lgkmcnt(5)
	v_mfma_f32_32x32x16_bf16 v[50:65], v[200:203], v[216:219], v[50:65]
	ds_read_b128 v[244:247], v0 offset:8192
	v_mfma_f32_32x32x16_bf16 v[34:49], v[204:207], v[216:219], v[34:49]
	ds_read_b128 v[248:251], v0 offset:12288
	s_waitcnt lgkmcnt(6)
	v_mfma_f32_32x32x16_bf16 v[18:33], v[200:203], v[220:223], v[18:33]
	v_mfma_f32_32x32x16_bf16 v[2:17], v[204:207], v[220:223], v[2:17]
	s_waitcnt vmcnt(0)
	s_waitcnt vmcnt(0) lgkmcnt(0)
	s_barrier
	s_cbranch_scc1 .Lgemm_exit_1371
	s_and_b32 s17, s16, 0x10000
	s_xor_b32 s43, s17, 0x10000
	s_add_i32 s43, s43, 0
	s_add_i32 s17, s17, 0
	v_add_u32_e32 v0, s17, v174
	v_add_u32_e32 v175, v0, v170
	v_add_u32_e32 v0, v0, v169
	ds_read_b128 v[200:203], v175 offset:32768
	ds_read_b128 v[204:207], v175 offset:36864
	ds_read_b128 v[208:211], v0
	ds_read_b128 v[212:215], v0 offset:4096
	ds_read_b128 v[216:219], v0 offset:8192
	ds_read_b128 v[220:223], v0 offset:12288
	v_mfma_f32_32x32x16_bf16 v[114:129], v[224:227], v[232:235], v[114:129]
	s_add_i32 s64, s43, 0x8000
	s_add_i32 m0, s43, s60
	v_lshl_add_u64 v[176:177], v[152:153], 0, s[10:11]
	global_load_lds_dwordx4 v[176:177], off
	v_mfma_f32_32x32x16_bf16 v[98:113], v[228:231], v[232:235], v[98:113]
	s_add_i32 m0, s43, s61
	v_lshl_add_u64 v[176:177], v[150:151], 0, s[10:11]
	global_load_lds_dwordx4 v[176:177], off
	s_add_i32 m0, s43, s62
	v_mfma_f32_32x32x16_bf16 v[82:97], v[224:227], v[240:243], v[82:97]
	v_lshl_add_u64 v[176:177], v[148:149], 0, s[10:11]
	global_load_lds_dwordx4 v[176:177], off
	s_add_i32 m0, s43, s63
	v_lshl_add_u64 v[176:177], v[146:147], 0, s[10:11]
	v_mfma_f32_32x32x16_bf16 v[66:81], v[228:231], v[240:243], v[66:81]
	global_load_lds_dwordx4 v[176:177], off
	s_add_i32 m0, s64, s60
	v_lshl_add_u64 v[176:177], v[144:145], 0, s[10:11]
	global_load_lds_dwordx4 v[176:177], off
	v_mfma_f32_32x32x16_bf16 v[50:65], v[224:227], v[244:247], v[50:65]
	s_add_i32 m0, s64, s61
	v_lshl_add_u64 v[176:177], v[142:143], 0, s[10:11]
	global_load_lds_dwordx4 v[176:177], off
	s_add_i32 m0, s64, s62
	v_mfma_f32_32x32x16_bf16 v[34:49], v[228:231], v[244:247], v[34:49]
	v_lshl_add_u64 v[176:177], v[140:141], 0, s[10:11]
	global_load_lds_dwordx4 v[176:177], off
	s_add_i32 m0, s64, s63
	v_lshl_add_u64 v[176:177], v[138:139], 0, s[10:11]
	v_mfma_f32_32x32x16_bf16 v[18:33], v[224:227], v[248:251], v[18:33]
	global_load_lds_dwordx4 v[176:177], off
	v_mfma_f32_32x32x16_bf16 v[2:17], v[228:231], v[248:251], v[2:17]
	s_branch .Lgemm_rot_1371
